# LN2 GEMM: K order rotated per row-block group (tm&7)*8 stages so the 8 XCDs stream different K offsets
# speedup vs baseline: 1.0227x; 1.0045x over previous
.LBB0_412:
	s_mul_hi_i32 s13, s70, 0x2aaaaaab
	s_lshr_b32 s14, s13, 31
	s_ashr_i32 s35, s13, 2
	s_add_i32 s35, s35, s14
	s_mul_i32 s13, s35, 24
	s_sub_i32 s60, s70, s13
	s_and_b32 s13, s60, 7
	s_lshl_b32 s13, s13, 10
	s_lshl_b32 s22, s60, 8
	s_ashr_i32 s23, s22, 31
	s_lshl_b64 s[36:37], s[22:23], 13
	s_or_b32 s36, s36, s13
	s_mov_b32 m0, s8
	v_lshl_add_u64 v[2:3], v[100:101], 0, s[36:37]
	s_mov_b64 s[50:51], 0x10000
	s_lshl_b32 s26, s35, 7
	global_load_lds_dwordx4 v[2:3], off
	v_lshl_add_u64 v[6:7], v[2:3], 0, s[50:51]
	s_add_i32 m0, s8, 0x400
	s_mov_b64 s[52:53], 0x20000
	s_ashr_i32 s27, s26, 31
	global_load_lds_dwordx4 v[6:7], off
	v_lshl_add_u64 v[6:7], v[2:3], 0, s[52:53]
	s_add_i32 m0, s8, 0x800
	s_mov_b64 s[52:53], 0x30000
	s_lshl_b64 s[48:49], s[26:27], 13
	s_or_b32 s48, s48, s13
	global_load_lds_dwordx4 v[6:7], off
	v_lshl_add_u64 v[6:7], v[2:3], 0, s[52:53]
	s_add_i32 m0, s8, 0xc00
	v_lshl_add_u64 v[4:5], v[102:103], 0, s[48:49]
	global_load_lds_dwordx4 v[6:7], off
	s_add_i32 m0, s9, 0x8000
	v_lshl_add_u64 v[6:7], v[4:5], 0, s[50:51]
	global_load_lds_dwordx4 v[4:5], off
	s_add_i32 m0, s9, 0x8400
	s_mov_b64 s[50:51], 0x10080
	global_load_lds_dwordx4 v[6:7], off
	v_lshl_add_u64 v[6:7], v[2:3], 0, s[2:3]
	s_add_i32 m0, s8, 0xc000
	s_mov_b64 s[52:53], 0x20080
	global_load_lds_dwordx4 v[6:7], off
	v_lshl_add_u64 v[6:7], v[2:3], 0, s[50:51]
	s_add_i32 m0, s8, 0xc400
	s_mov_b64 s[54:55], 0x10100
	global_load_lds_dwordx4 v[6:7], off
	v_lshl_add_u64 v[6:7], v[2:3], 0, s[52:53]
	s_add_i32 m0, s8, 0xc800
	s_mov_b64 s[52:53], 0x30080
	global_load_lds_dwordx4 v[6:7], off
	v_lshl_add_u64 v[6:7], v[2:3], 0, s[52:53]
	s_add_i32 m0, s8, 0xcc00
	s_mov_b64 s[52:53], 0x20100
	global_load_lds_dwordx4 v[6:7], off
	v_lshl_add_u64 v[6:7], v[4:5], 0, s[2:3]
	s_add_i32 m0, s9, 0x14000
	v_add_u32_e32 v172, v114, v115
	global_load_lds_dwordx4 v[6:7], off
	v_lshl_add_u64 v[6:7], v[4:5], 0, s[50:51]
	s_add_i32 m0, s9, 0x14400
	s_mov_b64 s[50:51], 0x100
	global_load_lds_dwordx4 v[6:7], off
	v_lshl_add_u64 v[6:7], v[2:3], 0, s[50:51]
	s_add_i32 m0, s8, 0x18000
	v_add_u32_e32 v173, v116, v115
	global_load_lds_dwordx4 v[6:7], off
	v_lshl_add_u64 v[6:7], v[2:3], 0, s[54:55]
	s_add_i32 m0, s8, 0x18400
	v_mov_b32_e32 v38, 0
	global_load_lds_dwordx4 v[6:7], off
	v_lshl_add_u64 v[6:7], v[2:3], 0, s[52:53]
	s_add_i32 m0, s8, 0x18800
	s_mov_b64 s[52:53], 0x30100
	global_load_lds_dwordx4 v[6:7], off
	v_lshl_add_u64 v[2:3], v[2:3], 0, s[52:53]
	s_add_i32 m0, s8, 0x18c00
	v_lshl_add_u64 v[108:109], v[104:105], 0, s[36:37]
	global_load_lds_dwordx4 v[2:3], off
	v_lshl_add_u64 v[2:3], v[4:5], 0, s[50:51]
	s_add_i32 m0, s9, 0x20000
	v_lshl_add_u64 v[110:111], v[106:107], 0, s[48:49]
	global_load_lds_dwordx4 v[2:3], off
	v_lshl_add_u64 v[2:3], v[4:5], 0, s[54:55]
	s_add_i32 m0, s9, 0x20400
	s_lshr_b32 s55, s13, 7
	s_sub_i32 s55, 61, s55
	s_mov_b32 s13, -1
	global_load_lds_dwordx4 v[2:3], off
	s_waitcnt vmcnt(12)
	s_waitcnt lgkmcnt(0)
	s_barrier
	ds_read_b128 v[30:33], v172
	ds_read_b128 v[26:29], v173 offset:2048
	s_waitcnt vmcnt(0)
	ds_read_b128 v[14:17], v173 offset:4096
	ds_read_b128 v[2:5], v173 offset:6144
	ds_read_b128 v[22:25], v161 offset:32768
	ds_read_b128 v[18:21], v164 offset:34816
	ds_read_b128 v[10:13], v164 offset:36864
	ds_read_b128 v[6:9], v164 offset:38912
	s_mov_b32 s14, 0
	s_mov_b32 s19, 1
	s_mov_b32 s23, 0
	v_mov_b32_e32 v39, v38
	v_mov_b32_e32 v40, v38
	v_mov_b32_e32 v41, v38
	v_mov_b32_e32 v42, v38
	v_mov_b32_e32 v43, v38
	v_mov_b32_e32 v44, v38
	v_mov_b32_e32 v45, v38
	v_mov_b32_e32 v46, v38
	v_mov_b32_e32 v47, v38
	v_mov_b32_e32 v48, v38
	v_mov_b32_e32 v49, v38
	v_mov_b32_e32 v50, v38
	v_mov_b32_e32 v51, v38
	v_mov_b32_e32 v52, v38
	v_mov_b32_e32 v53, v38
	v_mov_b32_e32 v54, v38
	v_mov_b32_e32 v55, v38
	v_mov_b32_e32 v56, v38
	v_mov_b32_e32 v57, v38
	v_mov_b32_e32 v58, v38
	v_mov_b32_e32 v59, v38
	v_mov_b32_e32 v60, v38
	v_mov_b32_e32 v61, v38
	v_mov_b32_e32 v62, v38
	v_mov_b32_e32 v63, v38
	v_mov_b32_e32 v64, v38
	v_mov_b32_e32 v65, v38
	v_mov_b32_e32 v66, v38
	v_mov_b32_e32 v67, v38
	v_mov_b32_e32 v68, v38
	v_mov_b32_e32 v69, v38
	v_mov_b32_e32 v78, v38
	v_mov_b32_e32 v79, v38
	v_mov_b32_e32 v80, v38
	v_mov_b32_e32 v81, v38
	v_mov_b32_e32 v70, v38
	v_mov_b32_e32 v71, v38
	v_mov_b32_e32 v72, v38
	v_mov_b32_e32 v73, v38
	v_mov_b32_e32 v74, v38
	v_mov_b32_e32 v75, v38
	v_mov_b32_e32 v76, v38
	v_mov_b32_e32 v77, v38
	v_mov_b32_e32 v34, v38
	v_mov_b32_e32 v35, v38
	v_mov_b32_e32 v36, v38
	v_mov_b32_e32 v37, v38
	v_mov_b32_e32 v86, v38
	v_mov_b32_e32 v87, v38
	v_mov_b32_e32 v88, v38
	v_mov_b32_e32 v89, v38
	v_mov_b32_e32 v94, v38
	v_mov_b32_e32 v95, v38
	v_mov_b32_e32 v96, v38
	v_mov_b32_e32 v97, v38
	v_mov_b32_e32 v90, v38
	v_mov_b32_e32 v91, v38
	v_mov_b32_e32 v92, v38
	v_mov_b32_e32 v93, v38
	v_mov_b32_e32 v82, v38
	v_mov_b32_e32 v83, v38
	v_mov_b32_e32 v84, v38
	v_mov_b32_e32 v85, v38
.LBB0_413:
	s_mul_hi_u32 s27, s23, 0xaaaaaaab
	s_lshr_b32 s27, s27, 1
	s_mul_i32 s27, s27, 0x24000
	s_waitcnt lgkmcnt(0)
	v_mfma_f32_16x16x32_bf16 v[66:69], v[22:25], v[26:29], v[66:69]
	v_add_u32_e32 v222, s14, v113
	s_mul_hi_u32 s34, s19, 0xaaaaaaab
	s_lshr_b32 s34, s34, 1
	v_mfma_f32_16x16x32_bf16 v[62:65], v[18:21], v[26:29], v[62:65]
	s_mul_i32 s34, s34, 0x24000
	v_subrev_u32_e32 v182, s34, v126
	v_subrev_u32_e32 v191, s34, v127
	v_mfma_f32_16x16x32_bf16 v[58:61], v[10:13], v[26:29], v[58:61]
	v_subrev_u32_e32 v201, s34, v128
	v_mfma_f32_16x16x32_bf16 v[54:57], v[6:9], v[26:29], v[54:57]
	v_subrev_u32_e32 v26, s27, v125
	v_mfma_f32_16x16x32_bf16 v[50:53], v[22:25], v[14:17], v[50:53]
	v_mfma_f32_16x16x32_bf16 v[46:49], v[18:21], v[14:17], v[46:49]
	v_mfma_f32_16x16x32_bf16 v[42:45], v[10:13], v[14:17], v[42:45]
	v_mfma_f32_16x16x32_bf16 v[38:41], v[6:9], v[14:17], v[38:41]
	v_subrev_u32_e32 v14, s27, v129
	v_add_u32_e32 v16, v222, v26
	v_add_u32_e32 v14, v222, v14
	v_mfma_f32_16x16x32_bf16 v[34:37], v[22:25], v[30:33], v[34:37]
	v_subrev_u32_e32 v15, s34, v130
	v_mfma_f32_16x16x32_bf16 v[86:89], v[22:25], v[2:5], v[86:89]
	ds_read_b128 v[22:25], v16
	ds_read_b128 v[174:177], v16 offset:2048
	ds_read_b128 v[178:181], v16 offset:4096
	ds_read_b128 v[202:205], v16 offset:6144
	ds_read_b128 v[206:209], v14 offset:32768
	ds_read_b128 v[210:213], v14 offset:34816
	ds_read_b128 v[214:217], v14 offset:36864
	ds_read_b128 v[218:221], v14 offset:38912
	v_mfma_f32_16x16x32_bf16 v[74:77], v[18:21], v[30:33], v[74:77]
	v_mfma_f32_16x16x32_bf16 v[70:73], v[10:13], v[30:33], v[70:73]
	v_mfma_f32_16x16x32_bf16 v[78:81], v[6:9], v[30:33], v[78:81]
	v_mfma_f32_16x16x32_bf16 v[94:97], v[18:21], v[2:5], v[94:97]
	v_mfma_f32_16x16x32_bf16 v[90:93], v[10:13], v[2:5], v[90:93]
	v_mfma_f32_16x16x32_bf16 v[82:85], v[6:9], v[2:5], v[82:85]
	s_add_i32 s27, s13, 4
	s_mul_i32 s34, s27, 0xab
	s_bfe_u32 s34, s34, 0x70009
	s_mul_i32 s34, s34, 3
	s_sub_i32 s27, s27, s34
	s_and_b32 s27, s27, 0xff
	s_mul_i32 s27, s27, 0xc000
	s_waitcnt vmcnt(6)
	v_add_u32_e32 v2, v222, v15
	v_add_u32_e32 v6, v222, v201
	s_waitcnt lgkmcnt(0)
	v_mfma_f32_16x16x32_bf16 v[66:69], v[206:209], v[174:177], v[66:69]
	s_mov_b64 s[36:37], 0xe1d8180
	s_add_i32 s34, s27, s8
	s_waitcnt lgkmcnt(0)
	v_mfma_f32_16x16x32_bf16 v[62:65], v[210:213], v[174:177], v[62:65]
	s_barrier
	ds_read_b128 v[30:33], v2
	ds_read_b128 v[26:29], v2 offset:2048
	ds_read_b128 v[14:17], v2 offset:4096
	ds_read_b128 v[2:5], v2 offset:6144
	v_mfma_f32_16x16x32_bf16 v[58:61], v[214:217], v[174:177], v[58:61]
	v_add_u32_e32 v7, v222, v191
	s_mov_b32 m0, s34
	s_add_i32 s27, s27, s9
	v_mfma_f32_16x16x32_bf16 v[54:57], v[218:221], v[174:177], v[54:57]
	v_lshl_add_u64 v[174:175], v[108:109], 0, v[98:99]
	v_lshl_add_u64 v[176:177], v[174:175], 0, s[36:37]
	s_mov_b64 s[36:37], 0xe1e8180
	v_mfma_f32_16x16x32_bf16 v[34:37], v[206:209], v[22:25], v[34:37]
	s_add_i32 s23, s23, 1
	v_mfma_f32_16x16x32_bf16 v[74:77], v[210:213], v[22:25], v[74:77]
	v_mfma_f32_16x16x32_bf16 v[70:73], v[214:217], v[22:25], v[70:73]
	v_mfma_f32_16x16x32_bf16 v[78:81], v[218:221], v[22:25], v[78:81]
	ds_read_b128 v[22:25], v6
	ds_read_b128 v[18:21], v7
	v_add_u32_e32 v6, v222, v182
	ds_read_b128 v[10:13], v6
	ds_read_b128 v[6:9], v6 offset:2048
	global_load_lds_dwordx4 v[176:177], off
	v_lshl_add_u64 v[176:177], v[174:175], 0, s[36:37]
	s_add_i32 m0, s34, 0x400
	s_mov_b64 s[36:37], 0xe1f8180
	global_load_lds_dwordx4 v[176:177], off
	v_lshl_add_u64 v[176:177], v[174:175], 0, s[36:37]
	s_add_i32 m0, s34, 0x800
	s_mov_b64 s[36:37], 0xe208180
	global_load_lds_dwordx4 v[176:177], off
	v_lshl_add_u64 v[174:175], v[174:175], 0, s[36:37]
	s_add_i32 m0, s34, 0xc00
	s_mov_b64 s[36:37], 0x4300180
	global_load_lds_dwordx4 v[174:175], off
	v_lshl_add_u64 v[174:175], v[110:111], 0, v[98:99]
	v_lshl_add_u64 v[176:177], v[174:175], 0, s[36:37]
	s_add_i32 m0, s27, 0x8000
	s_mov_b64 s[36:37], 0x4310180
	global_load_lds_dwordx4 v[176:177], off
	v_lshl_add_u64 v[174:175], v[174:175], 0, s[36:37]
	s_add_i32 m0, s27, 0x8400
	v_mfma_f32_16x16x32_bf16 v[50:53], v[206:209], v[178:181], v[50:53]
	global_load_lds_dwordx4 v[174:175], off
	v_mfma_f32_16x16x32_bf16 v[46:49], v[210:213], v[178:181], v[46:49]
	v_mfma_f32_16x16x32_bf16 v[42:45], v[214:217], v[178:181], v[42:45]
	v_mfma_f32_16x16x32_bf16 v[38:41], v[218:221], v[178:181], v[38:41]
	v_mfma_f32_16x16x32_bf16 v[86:89], v[206:209], v[202:205], v[86:89]
	v_mfma_f32_16x16x32_bf16 v[94:97], v[210:213], v[202:205], v[94:97]
	v_mfma_f32_16x16x32_bf16 v[90:93], v[214:217], v[202:205], v[90:93]
	v_mfma_f32_16x16x32_bf16 v[82:85], v[218:221], v[202:205], v[82:85]
	s_add_i32 s13, s13, 1
	s_add_i32 s14, s14, 0xc000
	s_add_i32 s19, s19, 1
	s_mov_b32 s36, 0xffffe080
	s_mov_b32 s37, -1
	s_cmp_eq_u32 s23, s55
	s_cselect_b64 s[36:37], s[36:37], s[2:3]
	v_lshl_add_u64 v[108:109], v[108:109], 0, s[36:37]
	v_lshl_add_u64 v[110:111], v[110:111], 0, s[36:37]
	s_cmp_eq_u32 s14, 0x2dc000
	s_cbranch_scc0 .LBB0_413
	s_waitcnt lgkmcnt(0)
	v_mfma_f32_16x16x32_bf16 v[34:37], v[22:25], v[30:33], v[34:37]
	v_mfma_f32_16x16x32_bf16 v[74:77], v[18:21], v[30:33], v[74:77]
	v_mfma_f32_16x16x32_bf16 v[70:73], v[10:13], v[30:33], v[70:73]
	v_mfma_f32_16x16x32_bf16 v[30:33], v[6:9], v[30:33], v[78:81]
	v_mfma_f32_16x16x32_bf16 v[66:69], v[22:25], v[26:29], v[66:69]
	v_mfma_f32_16x16x32_bf16 v[62:65], v[18:21], v[26:29], v[62:65]
	v_mfma_f32_16x16x32_bf16 v[58:61], v[10:13], v[26:29], v[58:61]
	v_mfma_f32_16x16x32_bf16 v[26:29], v[6:9], v[26:29], v[54:57]
	v_mfma_f32_16x16x32_bf16 v[50:53], v[22:25], v[14:17], v[50:53]
	v_mfma_f32_16x16x32_bf16 v[46:49], v[18:21], v[14:17], v[46:49]
	v_mfma_f32_16x16x32_bf16 v[42:45], v[10:13], v[14:17], v[42:45]
	v_mfma_f32_16x16x32_bf16 v[14:17], v[6:9], v[14:17], v[38:41]
	v_mfma_f32_16x16x32_bf16 v[22:25], v[22:25], v[2:5], v[86:89]
	s_nop 1
	ds_read_b128 v[38:41], v131
	ds_read_b128 v[54:57], v132 offset:2048
	ds_read_b128 v[78:81], v132 offset:4096
	ds_read_b128 v[86:89], v132 offset:6144
	v_mfma_f32_16x16x32_bf16 v[18:21], v[18:21], v[2:5], v[94:97]
	v_mfma_f32_16x16x32_bf16 v[10:13], v[10:13], v[2:5], v[90:93]
	s_nop 2
	ds_read_b128 v[90:93], v133 offset:32768
	ds_read_b128 v[94:97], v134 offset:34816
	ds_read_b128 v[108:111], v134 offset:36864
	ds_read_b128 v[174:177], v134 offset:38912
	v_mfma_f32_16x16x32_bf16 v[2:5], v[6:9], v[2:5], v[82:85]
	s_waitcnt lgkmcnt(0)
	v_mfma_f32_16x16x32_bf16 v[6:9], v[90:93], v[38:41], v[34:37]
	s_waitcnt vmcnt(6)
	s_waitcnt lgkmcnt(0)
	s_barrier
	v_mfma_f32_16x16x32_bf16 v[34:37], v[94:97], v[38:41], v[74:77]
	v_mfma_f32_16x16x32_bf16 v[70:73], v[108:111], v[38:41], v[70:73]
	v_mfma_f32_16x16x32_bf16 v[30:33], v[174:177], v[38:41], v[30:33]
	v_mfma_f32_16x16x32_bf16 v[38:41], v[90:93], v[54:57], v[66:69]
	v_mfma_f32_16x16x32_bf16 v[62:65], v[94:97], v[54:57], v[62:65]
	v_mfma_f32_16x16x32_bf16 v[58:61], v[108:111], v[54:57], v[58:61]
	v_mfma_f32_16x16x32_bf16 v[26:29], v[174:177], v[54:57], v[26:29]
	v_add_u32_e32 v54, v124, v115
	ds_read_b128 v[54:57], v54
	ds_read_b128 v[66:69], v135 offset:2048
	v_mfma_f32_16x16x32_bf16 v[50:53], v[90:93], v[78:81], v[50:53]
	v_mfma_f32_16x16x32_bf16 v[46:49], v[94:97], v[78:81], v[46:49]
	v_mfma_f32_16x16x32_bf16 v[42:45], v[108:111], v[78:81], v[42:45]
	v_mfma_f32_16x16x32_bf16 v[22:25], v[90:93], v[86:89], v[22:25]
	v_add_u32_e32 v90, 0x20800, v164
	v_mfma_f32_16x16x32_bf16 v[18:21], v[94:97], v[86:89], v[18:21]
	v_add_u32_e32 v94, 0x21000, v164
	v_mfma_f32_16x16x32_bf16 v[10:13], v[108:111], v[86:89], v[10:13]
	v_add_u32_e32 v108, 0x21800, v164
	v_mfma_f32_16x16x32_bf16 v[14:17], v[174:177], v[78:81], v[14:17]
	ds_read_b128 v[74:77], v135 offset:4096
	ds_read_b128 v[78:81], v135 offset:6144
	ds_read_b128 v[82:85], v163
	ds_read_b128 v[90:93], v90
	ds_read_b128 v[94:97], v94
	ds_read_b128 v[108:111], v108
	v_mfma_f32_16x16x32_bf16 v[2:5], v[174:177], v[86:89], v[2:5]
	s_waitcnt lgkmcnt(0)
	v_mfma_f32_16x16x32_bf16 v[6:9], v[82:85], v[54:57], v[6:9]
	v_mfma_f32_16x16x32_bf16 v[34:37], v[90:93], v[54:57], v[34:37]
	v_mfma_f32_16x16x32_bf16 v[70:73], v[94:97], v[54:57], v[70:73]
	v_mfma_f32_16x16x32_bf16 v[30:33], v[108:111], v[54:57], v[30:33]
	v_mfma_f32_16x16x32_bf16 v[54:57], v[90:93], v[66:69], v[62:65]
	s_nop 2
	v_add_u32_e32 v62, v124, v119
	v_mfma_f32_16x16x32_bf16 v[38:41], v[82:85], v[66:69], v[38:41]
	v_mfma_f32_16x16x32_bf16 v[58:61], v[94:97], v[66:69], v[58:61]
	v_mfma_f32_16x16x32_bf16 v[26:29], v[108:111], v[66:69], v[26:29]
	v_mfma_f32_16x16x32_bf16 v[50:53], v[82:85], v[74:77], v[50:53]
	v_mfma_f32_16x16x32_bf16 v[46:49], v[90:93], v[74:77], v[46:49]
	v_mfma_f32_16x16x32_bf16 v[42:45], v[94:97], v[74:77], v[42:45]
	v_mfma_f32_16x16x32_bf16 v[14:17], v[108:111], v[74:77], v[14:17]
	v_mfma_f32_16x16x32_bf16 v[22:25], v[82:85], v[78:81], v[22:25]
	ds_read_b128 v[62:65], v62
	ds_read_b128 v[66:69], v165
	ds_read_b128 v[74:77], v166
	ds_read_b128 v[82:85], v167
	v_mfma_f32_16x16x32_bf16 v[18:21], v[90:93], v[78:81], v[18:21]
	v_mfma_f32_16x16x32_bf16 v[10:13], v[94:97], v[78:81], v[10:13]
	ds_read_b128 v[86:89], v168
	ds_read_b128 v[90:93], v169
	ds_read_b128 v[94:97], v170
	ds_read_b128 v[174:177], v171
	v_mfma_f32_16x16x32_bf16 v[2:5], v[108:111], v[78:81], v[2:5]
	s_waitcnt vmcnt(0)
	s_waitcnt lgkmcnt(0)
	v_mfma_f32_16x16x32_bf16 v[6:9], v[86:89], v[62:65], v[6:9]
	s_waitcnt lgkmcnt(0)
	s_barrier
	v_mfma_f32_16x16x32_bf16 v[34:37], v[90:93], v[62:65], v[34:37]
	v_mfma_f32_16x16x32_bf16 v[70:73], v[94:97], v[62:65], v[70:73]
	v_mfma_f32_16x16x32_bf16 v[30:33], v[174:177], v[62:65], v[30:33]
	v_mfma_f32_16x16x32_bf16 v[38:41], v[86:89], v[66:69], v[38:41]
	v_mfma_f32_16x16x32_bf16 v[54:57], v[90:93], v[66:69], v[54:57]
	v_mfma_f32_16x16x32_bf16 v[58:61], v[94:97], v[66:69], v[58:61]
	v_mfma_f32_16x16x32_bf16 v[26:29], v[174:177], v[66:69], v[26:29]
	v_mfma_f32_16x16x32_bf16 v[50:53], v[86:89], v[74:77], v[50:53]
	v_mfma_f32_16x16x32_bf16 v[46:49], v[90:93], v[74:77], v[46:49]
	v_mfma_f32_16x16x32_bf16 v[42:45], v[94:97], v[74:77], v[42:45]
	v_mfma_f32_16x16x32_bf16 v[14:17], v[174:177], v[74:77], v[14:17]
	ds_read_b128 v[62:65], v164 offset:38912
	ds_read_b128 v[66:69], v164 offset:36864
	ds_read_b128 v[74:77], v164 offset:34816
	ds_read_b128 v[78:81], v161 offset:32768
	v_mfma_f32_16x16x32_bf16 v[22:25], v[86:89], v[82:85], v[22:25]
	v_mfma_f32_16x16x32_bf16 v[18:21], v[90:93], v[82:85], v[18:21]
	v_mfma_f32_16x16x32_bf16 v[10:13], v[94:97], v[82:85], v[10:13]
	ds_read_b128 v[86:89], v173 offset:6144
	ds_read_b128 v[90:93], v173 offset:4096
	ds_read_b128 v[94:97], v173 offset:2048
	ds_read_b128 v[108:111], v172
	v_mfma_f32_16x16x32_bf16 v[2:5], v[174:177], v[82:85], v[2:5]
	s_waitcnt lgkmcnt(0)
	v_mfma_f32_16x16x32_bf16 v[38:41], v[78:81], v[94:97], v[38:41]
	v_add_u32_e32 v82, v114, v119
	v_add_u32_e32 v172, v118, v119
	v_mfma_f32_16x16x32_bf16 v[54:57], v[74:77], v[94:97], v[54:57]
	v_mfma_f32_16x16x32_bf16 v[58:61], v[66:69], v[94:97], v[58:61]
	v_mfma_f32_16x16x32_bf16 v[26:29], v[62:65], v[94:97], v[26:29]
	v_add_u32_e32 v94, v117, v119
	v_mfma_f32_16x16x32_bf16 v[50:53], v[78:81], v[90:93], v[50:53]
	v_mfma_f32_16x16x32_bf16 v[46:49], v[74:77], v[90:93], v[46:49]
	v_mfma_f32_16x16x32_bf16 v[42:45], v[66:69], v[90:93], v[42:45]
	v_mfma_f32_16x16x32_bf16 v[14:17], v[62:65], v[90:93], v[14:17]
	v_add_u32_e32 v90, v116, v119
	v_mfma_f32_16x16x32_bf16 v[6:9], v[78:81], v[108:111], v[6:9]
	v_mfma_f32_16x16x32_bf16 v[34:37], v[74:77], v[108:111], v[34:37]
	v_mfma_f32_16x16x32_bf16 v[70:73], v[66:69], v[108:111], v[70:73]
	v_mfma_f32_16x16x32_bf16 v[30:33], v[62:65], v[108:111], v[30:33]
	v_mfma_f32_16x16x32_bf16 v[78:81], v[78:81], v[86:89], v[22:25]
	s_nop 2
	ds_read_b128 v[22:25], v82
	ds_read_b128 v[82:85], v90 offset:2048
	v_mfma_f32_16x16x32_bf16 v[74:77], v[74:77], v[86:89], v[18:21]
	s_nop 2
	ds_read_b128 v[18:21], v90 offset:4096
	ds_read_b128 v[90:93], v90 offset:6144
	v_mfma_f32_16x16x32_bf16 v[66:69], v[66:69], v[86:89], v[10:13]
	s_nop 2
	ds_read_b128 v[10:13], v94 offset:32768
	ds_read_b128 v[94:97], v172 offset:34816
	ds_read_b128 v[108:111], v172 offset:36864
	ds_read_b128 v[172:175], v172 offset:38912
	v_mfma_f32_16x16x32_bf16 v[2:5], v[62:65], v[86:89], v[2:5]
	s_waitcnt vmcnt(0)
	s_waitcnt lgkmcnt(0)
	v_mfma_f32_16x16x32_bf16 v[2:5], v[172:175], v[90:93], v[2:5]
	s_waitcnt lgkmcnt(0)
	s_barrier
	v_mfma_f32_16x16x32_bf16 v[62:65], v[10:13], v[22:25], v[6:9]
	v_mfma_f32_16x16x32_bf16 v[86:89], v[94:97], v[22:25], v[34:37]
	v_mfma_f32_16x16x32_bf16 v[70:73], v[108:111], v[22:25], v[70:73]
	v_mfma_f32_16x16x32_bf16 v[176:179], v[172:175], v[22:25], v[30:33]
	v_mfma_f32_16x16x32_bf16 v[202:205], v[10:13], v[82:85], v[38:41]
	v_mfma_f32_16x16x32_bf16 v[54:57], v[94:97], v[82:85], v[54:57]
	v_mfma_f32_16x16x32_bf16 v[58:61], v[108:111], v[82:85], v[58:61]
	v_mfma_f32_16x16x32_bf16 v[34:37], v[172:175], v[82:85], v[26:29]
	v_mfma_f32_16x16x32_bf16 v[30:33], v[10:13], v[18:21], v[50:53]
	v_mfma_f32_16x16x32_bf16 v[26:29], v[94:97], v[18:21], v[46:49]
	v_mfma_f32_16x16x32_bf16 v[22:25], v[108:111], v[18:21], v[42:45]
	v_mfma_f32_16x16x32_bf16 v[18:21], v[172:175], v[18:21], v[14:17]
	v_mfma_f32_16x16x32_bf16 v[14:17], v[10:13], v[90:93], v[78:81]
	v_mfma_f32_16x16x32_bf16 v[10:13], v[94:97], v[90:93], v[74:77]
	v_mfma_f32_16x16x32_bf16 v[6:9], v[108:111], v[90:93], v[66:69]
	s_mul_hi_i32 s54, s70, 0x2aaaaaab
	s_lshr_b32 s55, s54, 31
	s_ashr_i32 s54, s54, 2
	s_add_i32 s13, s54, s55
	s_mul_i32 s54, s13, 24
	s_sub_i32 s14, s70, s54
	v_readfirstlane_b32 s54, v137
	s_lshr_b32 s54, s54, 6
	s_and_b32 s19, s54, 1
	s_lshr_b32 s54, s54, 1
	s_lshl_b32 s54, s54, 6
	s_lshl_b32 s50, s14, 8
	s_add_i32 s50, s50, s54
	s_lshl_b32 s51, s13, 7
	s_lshl_b32 s54, s19, 6
	s_add_i32 s51, s51, s54
	s_add_i32 s54, s50, 0xfffff000
	s_ashr_i32 s54, s54, 10
	s_add_i32 s54, s54, 1
	s_cmpk_lt_i32 s50, 0x1000
	s_cselect_b32 s52, 0, s54
	v_readlane_b32 s53, v255, 40
	v_and_b32_e32 v250, 63, v137
	v_and_b32_e32 v251, 15, v250
	v_lshrrev_b32_e32 v252, 4, v250
	s_mul_i32 s54, s53, 3
	s_add_i32 s54, s54, s52
	s_mul_i32 s54, s54, 0x6000
	s_add_u32 s22, s94, 0x6300000
	s_addc_u32 s23, s95, 0
	s_add_u32 s22, s22, s54
	s_addc_u32 s23, s23, 0
	s_add_u32 s26, s94, 0x6348000
	s_addc_u32 s27, s95, 0
	v_add_u32_e32 v242, s50, v251
	v_lshlrev_b32_e32 v242, 12, v242
	s_lshl_b32 s54, s51, 2
	v_lshl_add_u32 v242, v252, 4, v242
	v_add_u32_e32 v242, s54, v242
	s_add_i32 s55, s51, 5120
	s_lshl_b32 s55, s55, 2
	v_lshl_add_u32 v246, v252, 4, s55
	v_add_u32_e32 v243, 0x10000, v242
	v_add_u32_e32 v244, 0x20000, v242
	v_add_u32_e32 v245, 0x30000, v242
	global_load_dwordx4 v[226:229], v246, s[22:23]
	global_load_dwordx4 v[230:233], v246, s[22:23] offset:64
	global_load_dwordx4 v[234:237], v246, s[22:23] offset:128
	global_load_dwordx4 v[238:241], v246, s[22:23] offset:192
	global_load_dwordx4 v[38:41], v242, s[26:27]
	global_load_dwordx4 v[42:45], v242, s[26:27] offset:64
	global_load_dwordx4 v[46:49], v242, s[26:27] offset:128
	global_load_dwordx4 v[50:53], v242, s[26:27] offset:192
	global_load_dwordx4 v[66:69], v243, s[26:27]
	global_load_dwordx4 v[74:77], v243, s[26:27] offset:64
	global_load_dwordx4 v[78:81], v243, s[26:27] offset:128
	global_load_dwordx4 v[82:85], v243, s[26:27] offset:192
	global_load_dwordx4 v[90:93], v244, s[26:27]
	global_load_dwordx4 v[94:97], v244, s[26:27] offset:64
	global_load_dwordx4 v[108:111], v244, s[26:27] offset:128
	global_load_dwordx4 v[172:175], v244, s[26:27] offset:192
	global_load_dwordx4 v[206:209], v245, s[26:27]
	global_load_dwordx4 v[210:213], v245, s[26:27] offset:64
	global_load_dwordx4 v[214:217], v245, s[26:27] offset:128
	global_load_dwordx4 v[218:221], v245, s[26:27] offset:192
	v_mov_b32_e32 v248, 0x3fd744fd
	v_mov_b32_e32 v249, 0x3fd744fd
	s_waitcnt vmcnt(12)
	v_pk_mul_f32 v[38:39], v[38:39], v[248:249]
	v_pk_mul_f32 v[40:41], v[40:41], v[248:249]
	v_pk_fma_f32 v[62:63], v[62:63], v[226:227], v[38:39]
	v_pk_fma_f32 v[64:65], v[64:65], v[228:229], v[40:41]
	v_pk_mul_f32 v[42:43], v[42:43], v[248:249]
	v_pk_mul_f32 v[44:45], v[44:45], v[248:249]
	v_pk_fma_f32 v[86:87], v[86:87], v[230:231], v[42:43]
	v_pk_fma_f32 v[88:89], v[88:89], v[232:233], v[44:45]
	v_pk_mul_f32 v[46:47], v[46:47], v[248:249]
	v_pk_mul_f32 v[48:49], v[48:49], v[248:249]
	v_pk_fma_f32 v[70:71], v[70:71], v[234:235], v[46:47]
	v_pk_fma_f32 v[72:73], v[72:73], v[236:237], v[48:49]
	v_pk_mul_f32 v[50:51], v[50:51], v[248:249]
	v_pk_mul_f32 v[52:53], v[52:53], v[248:249]
	v_pk_fma_f32 v[176:177], v[176:177], v[238:239], v[50:51]
	v_pk_fma_f32 v[178:179], v[178:179], v[240:241], v[52:53]
	s_waitcnt vmcnt(8)
	v_pk_mul_f32 v[66:67], v[66:67], v[248:249]
	v_pk_mul_f32 v[68:69], v[68:69], v[248:249]
	v_pk_fma_f32 v[202:203], v[202:203], v[226:227], v[66:67]
	v_pk_fma_f32 v[204:205], v[204:205], v[228:229], v[68:69]
	v_pk_mul_f32 v[74:75], v[74:75], v[248:249]
	v_pk_mul_f32 v[76:77], v[76:77], v[248:249]
	v_pk_fma_f32 v[54:55], v[54:55], v[230:231], v[74:75]
	v_pk_fma_f32 v[56:57], v[56:57], v[232:233], v[76:77]
	v_pk_mul_f32 v[78:79], v[78:79], v[248:249]
	v_pk_mul_f32 v[80:81], v[80:81], v[248:249]
	v_pk_fma_f32 v[58:59], v[58:59], v[234:235], v[78:79]
	v_pk_fma_f32 v[60:61], v[60:61], v[236:237], v[80:81]
	v_pk_mul_f32 v[82:83], v[82:83], v[248:249]
	v_pk_mul_f32 v[84:85], v[84:85], v[248:249]
	v_pk_fma_f32 v[34:35], v[34:35], v[238:239], v[82:83]
	v_pk_fma_f32 v[36:37], v[36:37], v[240:241], v[84:85]
	s_waitcnt vmcnt(4)
	v_pk_mul_f32 v[90:91], v[90:91], v[248:249]
	v_pk_mul_f32 v[92:93], v[92:93], v[248:249]
	v_pk_fma_f32 v[30:31], v[30:31], v[226:227], v[90:91]
	v_pk_fma_f32 v[32:33], v[32:33], v[228:229], v[92:93]
	v_pk_mul_f32 v[94:95], v[94:95], v[248:249]
	v_pk_mul_f32 v[96:97], v[96:97], v[248:249]
	v_pk_fma_f32 v[26:27], v[26:27], v[230:231], v[94:95]
	v_pk_fma_f32 v[28:29], v[28:29], v[232:233], v[96:97]
	v_pk_mul_f32 v[108:109], v[108:109], v[248:249]
	v_pk_mul_f32 v[110:111], v[110:111], v[248:249]
	v_pk_fma_f32 v[22:23], v[22:23], v[234:235], v[108:109]
	v_pk_fma_f32 v[24:25], v[24:25], v[236:237], v[110:111]
	v_pk_mul_f32 v[172:173], v[172:173], v[248:249]
	v_pk_mul_f32 v[174:175], v[174:175], v[248:249]
	v_pk_fma_f32 v[18:19], v[18:19], v[238:239], v[172:173]
	v_pk_fma_f32 v[20:21], v[20:21], v[240:241], v[174:175]
	s_waitcnt vmcnt(0)
	v_pk_mul_f32 v[206:207], v[206:207], v[248:249]
	v_pk_mul_f32 v[208:209], v[208:209], v[248:249]
	v_pk_fma_f32 v[14:15], v[14:15], v[226:227], v[206:207]
	v_pk_fma_f32 v[16:17], v[16:17], v[228:229], v[208:209]
	v_pk_mul_f32 v[210:211], v[210:211], v[248:249]
	v_pk_mul_f32 v[212:213], v[212:213], v[248:249]
	v_pk_fma_f32 v[10:11], v[10:11], v[230:231], v[210:211]
	v_pk_fma_f32 v[12:13], v[12:13], v[232:233], v[212:213]
	v_pk_mul_f32 v[214:215], v[214:215], v[248:249]
	v_pk_mul_f32 v[216:217], v[216:217], v[248:249]
	v_pk_fma_f32 v[6:7], v[6:7], v[234:235], v[214:215]
	v_pk_fma_f32 v[8:9], v[8:9], v[236:237], v[216:217]
	v_pk_mul_f32 v[218:219], v[218:219], v[248:249]
	v_pk_mul_f32 v[220:221], v[220:221], v[248:249]
	v_pk_fma_f32 v[2:3], v[2:3], v[238:239], v[218:219]
	v_pk_fma_f32 v[4:5], v[4:5], v[240:241], v[220:221]
	v_pk_mul_f32 v[208:209], v[62:63], v[62:63]
	v_pk_add_f32 v[206:207], v[62:63], v[64:65]
	v_pk_fma_f32 v[208:209], v[64:65], v[64:65], v[208:209]
	v_pk_add_f32 v[206:207], v[206:207], v[86:87]
	v_pk_fma_f32 v[208:209], v[86:87], v[86:87], v[208:209]
	v_pk_add_f32 v[206:207], v[206:207], v[88:89]
	v_pk_fma_f32 v[208:209], v[88:89], v[88:89], v[208:209]
	v_pk_add_f32 v[206:207], v[206:207], v[70:71]
	v_pk_fma_f32 v[208:209], v[70:71], v[70:71], v[208:209]
	v_pk_add_f32 v[206:207], v[206:207], v[72:73]
	v_pk_fma_f32 v[208:209], v[72:73], v[72:73], v[208:209]
	v_pk_add_f32 v[206:207], v[206:207], v[176:177]
	v_pk_fma_f32 v[208:209], v[176:177], v[176:177], v[208:209]
	v_pk_add_f32 v[206:207], v[206:207], v[178:179]
	v_pk_fma_f32 v[208:209], v[178:179], v[178:179], v[208:209]
	v_add_f32_e32 v206, v206, v207
	v_add_f32_e32 v208, v208, v209
	v_pk_mul_f32 v[212:213], v[202:203], v[202:203]
	v_pk_add_f32 v[210:211], v[202:203], v[204:205]
	v_pk_fma_f32 v[212:213], v[204:205], v[204:205], v[212:213]
	v_pk_add_f32 v[210:211], v[210:211], v[54:55]
	v_pk_fma_f32 v[212:213], v[54:55], v[54:55], v[212:213]
	v_pk_add_f32 v[210:211], v[210:211], v[56:57]
	v_pk_fma_f32 v[212:213], v[56:57], v[56:57], v[212:213]
	v_pk_add_f32 v[210:211], v[210:211], v[58:59]
	v_pk_fma_f32 v[212:213], v[58:59], v[58:59], v[212:213]
	v_pk_add_f32 v[210:211], v[210:211], v[60:61]
	v_pk_fma_f32 v[212:213], v[60:61], v[60:61], v[212:213]
	v_pk_add_f32 v[210:211], v[210:211], v[34:35]
	v_pk_fma_f32 v[212:213], v[34:35], v[34:35], v[212:213]
	v_pk_add_f32 v[210:211], v[210:211], v[36:37]
	v_pk_fma_f32 v[212:213], v[36:37], v[36:37], v[212:213]
	v_add_f32_e32 v210, v210, v211
	v_add_f32_e32 v212, v212, v213
	v_pk_mul_f32 v[216:217], v[30:31], v[30:31]
	v_pk_add_f32 v[214:215], v[30:31], v[32:33]
	v_pk_fma_f32 v[216:217], v[32:33], v[32:33], v[216:217]
	v_pk_add_f32 v[214:215], v[214:215], v[26:27]
	v_pk_fma_f32 v[216:217], v[26:27], v[26:27], v[216:217]
	v_pk_add_f32 v[214:215], v[214:215], v[28:29]
	v_pk_fma_f32 v[216:217], v[28:29], v[28:29], v[216:217]
	v_pk_add_f32 v[214:215], v[214:215], v[22:23]
	v_pk_fma_f32 v[216:217], v[22:23], v[22:23], v[216:217]
	v_pk_add_f32 v[214:215], v[214:215], v[24:25]
	v_pk_fma_f32 v[216:217], v[24:25], v[24:25], v[216:217]
	v_pk_add_f32 v[214:215], v[214:215], v[18:19]
	v_pk_fma_f32 v[216:217], v[18:19], v[18:19], v[216:217]
	v_pk_add_f32 v[214:215], v[214:215], v[20:21]
	v_pk_fma_f32 v[216:217], v[20:21], v[20:21], v[216:217]
	v_add_f32_e32 v214, v214, v215
	v_add_f32_e32 v216, v216, v217
	v_pk_mul_f32 v[220:221], v[14:15], v[14:15]
	v_pk_add_f32 v[218:219], v[14:15], v[16:17]
	v_pk_fma_f32 v[220:221], v[16:17], v[16:17], v[220:221]
	v_pk_add_f32 v[218:219], v[218:219], v[10:11]
	v_pk_fma_f32 v[220:221], v[10:11], v[10:11], v[220:221]
	v_pk_add_f32 v[218:219], v[218:219], v[12:13]
	v_pk_fma_f32 v[220:221], v[12:13], v[12:13], v[220:221]
	v_pk_add_f32 v[218:219], v[218:219], v[6:7]
	v_pk_fma_f32 v[220:221], v[6:7], v[6:7], v[220:221]
	v_pk_add_f32 v[218:219], v[218:219], v[8:9]
	v_pk_fma_f32 v[220:221], v[8:9], v[8:9], v[220:221]
	v_pk_add_f32 v[218:219], v[218:219], v[2:3]
	v_pk_fma_f32 v[220:221], v[2:3], v[2:3], v[220:221]
	v_pk_add_f32 v[218:219], v[218:219], v[4:5]
	v_pk_fma_f32 v[220:221], v[4:5], v[4:5], v[220:221]
	v_add_f32_e32 v218, v218, v219
	v_add_f32_e32 v220, v220, v221
	s_nop 1
	v_permlane16_swap_b32_e32 v206, v210
	v_permlane16_swap_b32_e32 v214, v218
	v_permlane16_swap_b32_e32 v208, v212
	v_permlane16_swap_b32_e32 v216, v220
	v_add_f32_e32 v206, v206, v210
	v_add_f32_e32 v214, v214, v218
	v_add_f32_e32 v208, v208, v212
	v_add_f32_e32 v216, v216, v220
	s_nop 1
	v_permlane32_swap_b32_e32 v206, v214
	v_permlane32_swap_b32_e32 v208, v216
	v_add_f32_e32 v248, v206, v214
	v_add_f32_e32 v249, v208, v216
	s_lshl_b32 s54, s53, 1
	s_add_i32 s54, s54, 0x2c7e91a1
	v_mov_b32_e32 v218, v248
	v_mov_b32_e32 v219, s54
	v_mov_b32_e32 v220, v249
	v_mov_b32_e32 v221, s54
	v_mov_b32_e32 v249, s54
	s_add_u32 s34, s94, 0xc9d8000
	s_addc_u32 s35, s95, 0
	v_add_u32_e32 v247, s50, v250
	v_lshlrev_b32_e32 v247, 4, v247
	s_lshl_b32 s55, s13, 1
	s_add_i32 s55, s55, s19
	s_mul_i32 s55, s55, 0x18000
	v_add_u32_e32 v246, s55, v247
	global_store_dwordx4 v246, v[218:221], s[34:35] sc1
	v_readlane_b32 s36, v253, 15
	v_readlane_b32 s37, v253, 16
	v_readlane_b32 s48, v253, 17
	v_readlane_b32 s49, v253, 18
	s_lshl_b32 s54, s53, 10
	s_add_i32 s54, s54, s51
	s_lshl_b32 s54, s54, 2
	v_lshl_add_u32 v222, v252, 4, s54
	s_nop 3
	global_load_dwordx4 v[66:69], v222, s[36:37]
	global_load_dwordx4 v[74:77], v222, s[36:37] offset:64
	global_load_dwordx4 v[78:81], v222, s[36:37] offset:128
	global_load_dwordx4 v[82:85], v222, s[36:37] offset:192
	global_load_dwordx4 v[90:93], v222, s[48:49]
	global_load_dwordx4 v[94:97], v222, s[48:49] offset:64
	global_load_dwordx4 v[108:111], v222, s[48:49] offset:128
	global_load_dwordx4 v[172:175], v222, s[48:49] offset:192
	s_add_u32 s22, s22, 0x12000
	s_addc_u32 s23, s23, 0
	s_add_i32 s54, s51, 0
	s_lshl_b32 s54, s54, 2
	v_lshl_add_u32 v222, v252, 4, s54
	v_add_u32_e32 v246, 0x1000, v222
	s_cmp_eq_u32 s53, 3
	s_cbranch_scc1 .Lln2_nosh
	global_load_dwordx4 v[38:41], v222, s[22:23]
	global_load_dwordx4 v[42:45], v222, s[22:23] offset:64
	global_load_dwordx4 v[46:49], v222, s[22:23] offset:128
	global_load_dwordx4 v[50:53], v222, s[22:23] offset:192
